# adaLN mod task: the 20 cond loads of the SiLU staging in flight together (were serialised), on top of the f32-MFMA filter output layer
# speedup vs baseline: 1.0417x; 1.0023x over previous
.LBB0_814:
	s_andn2_b64 vcc, exec, s[0:1]
	s_cbranch_vccnz .LBB0_828
	v_mov_b32_e32 v5, v151
	s_movk_i32 s0, 0x1400
	s_waitcnt vmcnt(63) expcnt(7) lgkmcnt(15)
	s_barrier
	s_nop 0
	v_cmp_gt_i32_e32 vcc, s0, v5
	s_and_saveexec_b64 s[0:1], vcc
	s_cbranch_execz .LBB0_822
	v_readlane_b32 s64, v252, 25
	v_readlane_b32 s65, v252, 26
	v_readlane_b32 s66, v252, 27
	v_readlane_b32 s67, v252, 28
	v_lshlrev_b32_e32 v4, 2, v151
	v_add_u32_e32 v30, 0x1000, v4
	v_add_u32_e32 v31, 0x2000, v4
	v_add_u32_e32 v32, 0x3000, v4
	s_nop 4
	global_load_dword v10, v4, s[66:67] offset:0
	global_load_dword v11, v4, s[66:67] offset:1024
	global_load_dword v12, v4, s[66:67] offset:2048
	global_load_dword v13, v4, s[66:67] offset:3072
	global_load_dword v14, v4, s[64:65] offset:0
	global_load_dword v15, v4, s[64:65] offset:1024
	global_load_dword v16, v4, s[64:65] offset:2048
	global_load_dword v17, v4, s[64:65] offset:3072
	global_load_dword v18, v30, s[64:65] offset:0
	global_load_dword v19, v30, s[64:65] offset:1024
	global_load_dword v20, v30, s[64:65] offset:2048
	global_load_dword v21, v30, s[64:65] offset:3072
	global_load_dword v22, v31, s[64:65] offset:0
	global_load_dword v23, v31, s[64:65] offset:1024
	global_load_dword v24, v31, s[64:65] offset:2048
	global_load_dword v25, v31, s[64:65] offset:3072
	global_load_dword v26, v32, s[64:65] offset:0
	global_load_dword v27, v32, s[64:65] offset:1024
	global_load_dword v28, v32, s[64:65] offset:2048
	global_load_dword v29, v32, s[64:65] offset:3072
	s_waitcnt vmcnt(19)
	v_mul_f32_e32 v2, 0xbfb8aa3b, v10
	v_exp_f32_e32 v2, v2
	s_nop 0
	v_add_f32_e32 v2, 1.0, v2
	v_div_scale_f32 v3, s[8:9], v2, v2, v10
	v_rcp_f32_e32 v6, v3
	s_nop 0
	v_fma_f32 v7, -v3, v6, 1.0
	v_fmac_f32_e32 v6, v7, v6
	v_div_scale_f32 v7, vcc, v10, v2, v10
	v_mul_f32_e32 v8, v7, v6
	v_fma_f32 v9, -v3, v8, v7
	v_fmac_f32_e32 v8, v9, v6
	v_fma_f32 v3, -v3, v8, v7
	v_div_fmas_f32 v3, v3, v6, v8
	v_div_fixup_f32 v0, v3, v2, v10
	ds_write_b32 v4, v0 offset:0
	s_waitcnt vmcnt(18)
	v_mul_f32_e32 v2, 0xbfb8aa3b, v11
	v_exp_f32_e32 v2, v2
	s_nop 0
	v_add_f32_e32 v2, 1.0, v2
	v_div_scale_f32 v3, s[8:9], v2, v2, v11
	v_rcp_f32_e32 v6, v3
	s_nop 0
	v_fma_f32 v7, -v3, v6, 1.0
	v_fmac_f32_e32 v6, v7, v6
	v_div_scale_f32 v7, vcc, v11, v2, v11
	v_mul_f32_e32 v8, v7, v6
	v_fma_f32 v9, -v3, v8, v7
	v_fmac_f32_e32 v8, v9, v6
	v_fma_f32 v3, -v3, v8, v7
	v_div_fmas_f32 v3, v3, v6, v8
	v_div_fixup_f32 v0, v3, v2, v11
	ds_write_b32 v4, v0 offset:1024
	s_waitcnt vmcnt(17)
	v_mul_f32_e32 v2, 0xbfb8aa3b, v12
	v_exp_f32_e32 v2, v2
	s_nop 0
	v_add_f32_e32 v2, 1.0, v2
	v_div_scale_f32 v3, s[8:9], v2, v2, v12
	v_rcp_f32_e32 v6, v3
	s_nop 0
	v_fma_f32 v7, -v3, v6, 1.0
	v_fmac_f32_e32 v6, v7, v6
	v_div_scale_f32 v7, vcc, v12, v2, v12
	v_mul_f32_e32 v8, v7, v6
	v_fma_f32 v9, -v3, v8, v7
	v_fmac_f32_e32 v8, v9, v6
	v_fma_f32 v3, -v3, v8, v7
	v_div_fmas_f32 v3, v3, v6, v8
	v_div_fixup_f32 v0, v3, v2, v12
	ds_write_b32 v4, v0 offset:2048
	s_waitcnt vmcnt(16)
	v_mul_f32_e32 v2, 0xbfb8aa3b, v13
	v_exp_f32_e32 v2, v2
	s_nop 0
	v_add_f32_e32 v2, 1.0, v2
	v_div_scale_f32 v3, s[8:9], v2, v2, v13
	v_rcp_f32_e32 v6, v3
	s_nop 0
	v_fma_f32 v7, -v3, v6, 1.0
	v_fmac_f32_e32 v6, v7, v6
	v_div_scale_f32 v7, vcc, v13, v2, v13
	v_mul_f32_e32 v8, v7, v6
	v_fma_f32 v9, -v3, v8, v7
	v_fmac_f32_e32 v8, v9, v6
	v_fma_f32 v3, -v3, v8, v7
	v_div_fmas_f32 v3, v3, v6, v8
	v_div_fixup_f32 v0, v3, v2, v13
	ds_write_b32 v4, v0 offset:3072
	s_waitcnt vmcnt(15)
	v_mul_f32_e32 v2, 0xbfb8aa3b, v14
	v_exp_f32_e32 v2, v2
	s_nop 0
	v_add_f32_e32 v2, 1.0, v2
	v_div_scale_f32 v3, s[8:9], v2, v2, v14
	v_rcp_f32_e32 v6, v3
	s_nop 0
	v_fma_f32 v7, -v3, v6, 1.0
	v_fmac_f32_e32 v6, v7, v6
	v_div_scale_f32 v7, vcc, v14, v2, v14
	v_mul_f32_e32 v8, v7, v6
	v_fma_f32 v9, -v3, v8, v7
	v_fmac_f32_e32 v8, v9, v6
	v_fma_f32 v3, -v3, v8, v7
	v_div_fmas_f32 v3, v3, v6, v8
	v_div_fixup_f32 v0, v3, v2, v14
	ds_write_b32 v4, v0 offset:4096
	s_waitcnt vmcnt(14)
	v_mul_f32_e32 v2, 0xbfb8aa3b, v15
	v_exp_f32_e32 v2, v2
	s_nop 0
	v_add_f32_e32 v2, 1.0, v2
	v_div_scale_f32 v3, s[8:9], v2, v2, v15
	v_rcp_f32_e32 v6, v3
	s_nop 0
	v_fma_f32 v7, -v3, v6, 1.0
	v_fmac_f32_e32 v6, v7, v6
	v_div_scale_f32 v7, vcc, v15, v2, v15
	v_mul_f32_e32 v8, v7, v6
	v_fma_f32 v9, -v3, v8, v7
	v_fmac_f32_e32 v8, v9, v6
	v_fma_f32 v3, -v3, v8, v7
	v_div_fmas_f32 v3, v3, v6, v8
	v_div_fixup_f32 v0, v3, v2, v15
	ds_write_b32 v4, v0 offset:5120
	s_waitcnt vmcnt(13)
	v_mul_f32_e32 v2, 0xbfb8aa3b, v16
	v_exp_f32_e32 v2, v2
	s_nop 0
	v_add_f32_e32 v2, 1.0, v2
	v_div_scale_f32 v3, s[8:9], v2, v2, v16
	v_rcp_f32_e32 v6, v3
	s_nop 0
	v_fma_f32 v7, -v3, v6, 1.0
	v_fmac_f32_e32 v6, v7, v6
	v_div_scale_f32 v7, vcc, v16, v2, v16
	v_mul_f32_e32 v8, v7, v6
	v_fma_f32 v9, -v3, v8, v7
	v_fmac_f32_e32 v8, v9, v6
	v_fma_f32 v3, -v3, v8, v7
	v_div_fmas_f32 v3, v3, v6, v8
	v_div_fixup_f32 v0, v3, v2, v16
	ds_write_b32 v4, v0 offset:6144
	s_waitcnt vmcnt(12)
	v_mul_f32_e32 v2, 0xbfb8aa3b, v17
	v_exp_f32_e32 v2, v2
	s_nop 0
	v_add_f32_e32 v2, 1.0, v2
	v_div_scale_f32 v3, s[8:9], v2, v2, v17
	v_rcp_f32_e32 v6, v3
	s_nop 0
	v_fma_f32 v7, -v3, v6, 1.0
	v_fmac_f32_e32 v6, v7, v6
	v_div_scale_f32 v7, vcc, v17, v2, v17
	v_mul_f32_e32 v8, v7, v6
	v_fma_f32 v9, -v3, v8, v7
	v_fmac_f32_e32 v8, v9, v6
	v_fma_f32 v3, -v3, v8, v7
	v_div_fmas_f32 v3, v3, v6, v8
	v_div_fixup_f32 v0, v3, v2, v17
	ds_write_b32 v4, v0 offset:7168
	s_waitcnt vmcnt(11)
	v_mul_f32_e32 v2, 0xbfb8aa3b, v18
	v_exp_f32_e32 v2, v2
	s_nop 0
	v_add_f32_e32 v2, 1.0, v2
	v_div_scale_f32 v3, s[8:9], v2, v2, v18
	v_rcp_f32_e32 v6, v3
	s_nop 0
	v_fma_f32 v7, -v3, v6, 1.0
	v_fmac_f32_e32 v6, v7, v6
	v_div_scale_f32 v7, vcc, v18, v2, v18
	v_mul_f32_e32 v8, v7, v6
	v_fma_f32 v9, -v3, v8, v7
	v_fmac_f32_e32 v8, v9, v6
	v_fma_f32 v3, -v3, v8, v7
	v_div_fmas_f32 v3, v3, v6, v8
	v_div_fixup_f32 v0, v3, v2, v18
	ds_write_b32 v4, v0 offset:8192
	s_waitcnt vmcnt(10)
	v_mul_f32_e32 v2, 0xbfb8aa3b, v19
	v_exp_f32_e32 v2, v2
	s_nop 0
	v_add_f32_e32 v2, 1.0, v2
	v_div_scale_f32 v3, s[8:9], v2, v2, v19
	v_rcp_f32_e32 v6, v3
	s_nop 0
	v_fma_f32 v7, -v3, v6, 1.0
	v_fmac_f32_e32 v6, v7, v6
	v_div_scale_f32 v7, vcc, v19, v2, v19
	v_mul_f32_e32 v8, v7, v6
	v_fma_f32 v9, -v3, v8, v7
	v_fmac_f32_e32 v8, v9, v6
	v_fma_f32 v3, -v3, v8, v7
	v_div_fmas_f32 v3, v3, v6, v8
	v_div_fixup_f32 v0, v3, v2, v19
	ds_write_b32 v4, v0 offset:9216
	s_waitcnt vmcnt(9)
	v_mul_f32_e32 v2, 0xbfb8aa3b, v20
	v_exp_f32_e32 v2, v2
	s_nop 0
	v_add_f32_e32 v2, 1.0, v2
	v_div_scale_f32 v3, s[8:9], v2, v2, v20
	v_rcp_f32_e32 v6, v3
	s_nop 0
	v_fma_f32 v7, -v3, v6, 1.0
	v_fmac_f32_e32 v6, v7, v6
	v_div_scale_f32 v7, vcc, v20, v2, v20
	v_mul_f32_e32 v8, v7, v6
	v_fma_f32 v9, -v3, v8, v7
	v_fmac_f32_e32 v8, v9, v6
	v_fma_f32 v3, -v3, v8, v7
	v_div_fmas_f32 v3, v3, v6, v8
	v_div_fixup_f32 v0, v3, v2, v20
	ds_write_b32 v4, v0 offset:10240
	s_waitcnt vmcnt(8)
	v_mul_f32_e32 v2, 0xbfb8aa3b, v21
	v_exp_f32_e32 v2, v2
	s_nop 0
	v_add_f32_e32 v2, 1.0, v2
	v_div_scale_f32 v3, s[8:9], v2, v2, v21
	v_rcp_f32_e32 v6, v3
	s_nop 0
	v_fma_f32 v7, -v3, v6, 1.0
	v_fmac_f32_e32 v6, v7, v6
	v_div_scale_f32 v7, vcc, v21, v2, v21
	v_mul_f32_e32 v8, v7, v6
	v_fma_f32 v9, -v3, v8, v7
	v_fmac_f32_e32 v8, v9, v6
	v_fma_f32 v3, -v3, v8, v7
	v_div_fmas_f32 v3, v3, v6, v8
	v_div_fixup_f32 v0, v3, v2, v21
	ds_write_b32 v4, v0 offset:11264
	s_waitcnt vmcnt(7)
	v_mul_f32_e32 v2, 0xbfb8aa3b, v22
	v_exp_f32_e32 v2, v2
	s_nop 0
	v_add_f32_e32 v2, 1.0, v2
	v_div_scale_f32 v3, s[8:9], v2, v2, v22
	v_rcp_f32_e32 v6, v3
	s_nop 0
	v_fma_f32 v7, -v3, v6, 1.0
	v_fmac_f32_e32 v6, v7, v6
	v_div_scale_f32 v7, vcc, v22, v2, v22
	v_mul_f32_e32 v8, v7, v6
	v_fma_f32 v9, -v3, v8, v7
	v_fmac_f32_e32 v8, v9, v6
	v_fma_f32 v3, -v3, v8, v7
	v_div_fmas_f32 v3, v3, v6, v8
	v_div_fixup_f32 v0, v3, v2, v22
	ds_write_b32 v4, v0 offset:12288
	s_waitcnt vmcnt(6)
	v_mul_f32_e32 v2, 0xbfb8aa3b, v23
	v_exp_f32_e32 v2, v2
	s_nop 0
	v_add_f32_e32 v2, 1.0, v2
	v_div_scale_f32 v3, s[8:9], v2, v2, v23
	v_rcp_f32_e32 v6, v3
	s_nop 0
	v_fma_f32 v7, -v3, v6, 1.0
	v_fmac_f32_e32 v6, v7, v6
	v_div_scale_f32 v7, vcc, v23, v2, v23
	v_mul_f32_e32 v8, v7, v6
	v_fma_f32 v9, -v3, v8, v7
	v_fmac_f32_e32 v8, v9, v6
	v_fma_f32 v3, -v3, v8, v7
	v_div_fmas_f32 v3, v3, v6, v8
	v_div_fixup_f32 v0, v3, v2, v23
	ds_write_b32 v4, v0 offset:13312
	s_waitcnt vmcnt(5)
	v_mul_f32_e32 v2, 0xbfb8aa3b, v24
	v_exp_f32_e32 v2, v2
	s_nop 0
	v_add_f32_e32 v2, 1.0, v2
	v_div_scale_f32 v3, s[8:9], v2, v2, v24
	v_rcp_f32_e32 v6, v3
	s_nop 0
	v_fma_f32 v7, -v3, v6, 1.0
	v_fmac_f32_e32 v6, v7, v6
	v_div_scale_f32 v7, vcc, v24, v2, v24
	v_mul_f32_e32 v8, v7, v6
	v_fma_f32 v9, -v3, v8, v7
	v_fmac_f32_e32 v8, v9, v6
	v_fma_f32 v3, -v3, v8, v7
	v_div_fmas_f32 v3, v3, v6, v8
	v_div_fixup_f32 v0, v3, v2, v24
	ds_write_b32 v4, v0 offset:14336
	s_waitcnt vmcnt(4)
	v_mul_f32_e32 v2, 0xbfb8aa3b, v25
	v_exp_f32_e32 v2, v2
	s_nop 0
	v_add_f32_e32 v2, 1.0, v2
	v_div_scale_f32 v3, s[8:9], v2, v2, v25
	v_rcp_f32_e32 v6, v3
	s_nop 0
	v_fma_f32 v7, -v3, v6, 1.0
	v_fmac_f32_e32 v6, v7, v6
	v_div_scale_f32 v7, vcc, v25, v2, v25
	v_mul_f32_e32 v8, v7, v6
	v_fma_f32 v9, -v3, v8, v7
	v_fmac_f32_e32 v8, v9, v6
	v_fma_f32 v3, -v3, v8, v7
	v_div_fmas_f32 v3, v3, v6, v8
	v_div_fixup_f32 v0, v3, v2, v25
	ds_write_b32 v4, v0 offset:15360
	s_waitcnt vmcnt(3)
	v_mul_f32_e32 v2, 0xbfb8aa3b, v26
	v_exp_f32_e32 v2, v2
	s_nop 0
	v_add_f32_e32 v2, 1.0, v2
	v_div_scale_f32 v3, s[8:9], v2, v2, v26
	v_rcp_f32_e32 v6, v3
	s_nop 0
	v_fma_f32 v7, -v3, v6, 1.0
	v_fmac_f32_e32 v6, v7, v6
	v_div_scale_f32 v7, vcc, v26, v2, v26
	v_mul_f32_e32 v8, v7, v6
	v_fma_f32 v9, -v3, v8, v7
	v_fmac_f32_e32 v8, v9, v6
	v_fma_f32 v3, -v3, v8, v7
	v_div_fmas_f32 v3, v3, v6, v8
	v_div_fixup_f32 v0, v3, v2, v26
	ds_write_b32 v4, v0 offset:16384
	s_waitcnt vmcnt(2)
	v_mul_f32_e32 v2, 0xbfb8aa3b, v27
	v_exp_f32_e32 v2, v2
	s_nop 0
	v_add_f32_e32 v2, 1.0, v2
	v_div_scale_f32 v3, s[8:9], v2, v2, v27
	v_rcp_f32_e32 v6, v3
	s_nop 0
	v_fma_f32 v7, -v3, v6, 1.0
	v_fmac_f32_e32 v6, v7, v6
	v_div_scale_f32 v7, vcc, v27, v2, v27
	v_mul_f32_e32 v8, v7, v6
	v_fma_f32 v9, -v3, v8, v7
	v_fmac_f32_e32 v8, v9, v6
	v_fma_f32 v3, -v3, v8, v7
	v_div_fmas_f32 v3, v3, v6, v8
	v_div_fixup_f32 v0, v3, v2, v27
	ds_write_b32 v4, v0 offset:17408
	s_waitcnt vmcnt(1)
	v_mul_f32_e32 v2, 0xbfb8aa3b, v28
	v_exp_f32_e32 v2, v2
	s_nop 0
	v_add_f32_e32 v2, 1.0, v2
	v_div_scale_f32 v3, s[8:9], v2, v2, v28
	v_rcp_f32_e32 v6, v3
	s_nop 0
	v_fma_f32 v7, -v3, v6, 1.0
	v_fmac_f32_e32 v6, v7, v6
	v_div_scale_f32 v7, vcc, v28, v2, v28
	v_mul_f32_e32 v8, v7, v6
	v_fma_f32 v9, -v3, v8, v7
	v_fmac_f32_e32 v8, v9, v6
	v_fma_f32 v3, -v3, v8, v7
	v_div_fmas_f32 v3, v3, v6, v8
	v_div_fixup_f32 v0, v3, v2, v28
	ds_write_b32 v4, v0 offset:18432
	s_waitcnt vmcnt(0)
	v_mul_f32_e32 v2, 0xbfb8aa3b, v29
	v_exp_f32_e32 v2, v2
	s_nop 0
	v_add_f32_e32 v2, 1.0, v2
	v_div_scale_f32 v3, s[8:9], v2, v2, v29
	v_rcp_f32_e32 v6, v3
	s_nop 0
	v_fma_f32 v7, -v3, v6, 1.0
	v_fmac_f32_e32 v6, v7, v6
	v_div_scale_f32 v7, vcc, v29, v2, v29
	v_mul_f32_e32 v8, v7, v6
	v_fma_f32 v9, -v3, v8, v7
	v_fmac_f32_e32 v8, v9, v6
	v_fma_f32 v3, -v3, v8, v7
	v_div_fmas_f32 v3, v3, v6, v8
	v_div_fixup_f32 v0, v3, v2, v29
	ds_write_b32 v4, v0 offset:19456
